# v005a plus: dilated far tiles pick the one-in-four score with lane-mask selects (v_cndmask) instead of one-hot multiply-adds
# speedup vs baseline: 1.0163x; 1.0000x over previous
.LBB0_253:
	s_or_b64 exec, exec, s[4:5]
	v_readlane_b32 s4, v254, 26
	v_readlane_b32 s5, v254, 27
	s_xor_b64 s[86:87], s[4:5], -1
	s_mov_b64 s[4:5], -1
	s_and_b64 vcc, exec, s[86:87]
	s_waitcnt lgkmcnt(0)
	s_barrier
	s_cbranch_vccz .LBB0_329
	v_readlane_b32 s4, v255, 46
	v_readlane_b32 s5, v255, 47
	s_andn2_b64 vcc, exec, s[4:5]
	s_cbranch_vccnz .LBB0_328
	s_mov_b32 s17, 0
	s_mov_b32 s88, 0x11111111
	s_mov_b32 s89, 0x11111111
	s_mov_b32 s90, 0x22222222
	s_mov_b32 s91, 0x22222222
	s_mov_b32 s92, 0x44444444
	s_mov_b32 s93, 0x44444444
	v_readlane_b32 s0, v253, 10
	s_branch .LBB0_257

.LBB0_289:
	s_and_b64 vcc, exec, s[4:5]
	s_cbranch_vccz .LBB0_293
	v_add_u32_e32 v70, s61, v234
	ds_read_b128 v[66:69], v70
	ds_read_b128 v[98:101], v70 offset:32
	ds_read_b128 v[102:105], v70 offset:64
	ds_read_b128 v[106:109], v70 offset:96
	v_add_u32_e32 v70, s62, v235
	s_nop 1
	ds_read_b64_tr_b16 v[94:95], v70
	ds_read_b64_tr_b16 v[96:97], v70 offset:1024
	ds_read_b64_tr_b16 v[92:93], v70 offset:1536
	ds_read_b64_tr_b16 v[90:91], v70 offset:512
	ds_read_b64_tr_b16 v[86:87], v70 offset:2048
	ds_read_b64_tr_b16 v[88:89], v70 offset:3072
	ds_read_b64_tr_b16 v[84:85], v70 offset:3584
	ds_read_b64_tr_b16 v[82:83], v70 offset:2560
	s_cmp_eq_u32 s12, s60
	s_cselect_b64 s[4:5], -1, 0
	s_waitcnt lgkmcnt(0)
	v_mfma_f32_32x32x16_bf16 v[66:81], v[66:69], v[126:129], 0
	s_and_b64 vcc, s[4:5], s[38:39]
	v_mfma_f32_32x32x16_bf16 v[66:81], v[98:101], v[122:125], v[66:81]
	v_mfma_f32_32x32x16_bf16 v[66:81], v[102:105], v[118:121], v[66:81]
	v_mfma_f32_32x32x16_bf16 v[66:81], v[106:109], v[114:117], v[66:81]
	s_nop 11
	v_cndmask_b32_e64 v98, v69, v68, s[92:93]
	v_cndmask_b32_e64 v99, v73, v72, s[92:93]
	v_cndmask_b32_e64 v100, v77, v76, s[92:93]
	v_cndmask_b32_e64 v101, v81, v80, s[92:93]
	v_cndmask_b32_e64 v98, v98, v67, s[90:91]
	v_cndmask_b32_e64 v99, v99, v71, s[90:91]
	v_cndmask_b32_e64 v100, v100, v75, s[90:91]
	v_cndmask_b32_e64 v101, v101, v79, s[90:91]
	v_cndmask_b32_e64 v66, v98, v66, s[88:89]
	v_cndmask_b32_e64 v67, v99, v70, s[88:89]
	v_cndmask_b32_e64 v68, v100, v74, s[88:89]
	v_cndmask_b32_e64 v69, v101, v78, s[88:89]
	v_fmamk_f32 v66, v66, 0x3e38aa3b, v214
	v_fmamk_f32 v67, v67, 0x3e38aa3b, v214
	v_fmamk_f32 v68, v68, 0x3e38aa3b, v214
	v_fmamk_f32 v69, v69, 0x3e38aa3b, v214
	v_cndmask_b32_e32 v66, v66, v229, vcc
	s_and_b64 vcc, s[4:5], s[40:41]
	v_cndmask_b32_e32 v67, v67, v229, vcc
	s_and_b64 vcc, s[4:5], s[42:43]
	v_cndmask_b32_e32 v68, v68, v229, vcc
	s_and_b64 vcc, s[4:5], s[44:45]
	v_cndmask_b32_e32 v69, v69, v229, vcc
	v_max_f32_e32 v70, v69, v69
	v_max_f32_e32 v71, v68, v68
	v_max_f32_e32 v70, v71, v70
	v_max3_f32 v70, v66, v67, v70
	v_cmp_gt_f32_e32 vcc, v70, v236
	s_cbranch_vccz .LBB0_292
	v_and_b32_e32 v72, 64, v228
	v_xor_b32_e32 v71, 32, v228
	v_add_u32_e32 v72, 64, v72
	v_cmp_lt_i32_e32 vcc, v71, v72
	s_nop 1
	v_cndmask_b32_e32 v71, v228, v71, vcc
	v_lshlrev_b32_e32 v71, 2, v71
	ds_bpermute_b32 v71, v71, v70
	v_max_f32_e32 v70, v70, v70
	s_waitcnt lgkmcnt(0)
	v_max_f32_e32 v71, v71, v71
	v_max_f32_e32 v70, v70, v71
	v_cmp_gt_f32_e32 vcc, v70, v236
	s_nop 1
	v_cndmask_b32_e32 v71, v223, v70, vcc
	v_sub_f32_e32 v70, v223, v71
	v_exp_f32_e32 v70, v70
	v_mov_b32_e32 v223, v71
	v_pk_mul_f32 v[64:65], v[64:65], v[70:71] op_sel_hi:[1,0]
	v_pk_mul_f32 v[62:63], v[62:63], v[70:71] op_sel_hi:[1,0]
	v_pk_mul_f32 v[60:61], v[60:61], v[70:71] op_sel_hi:[1,0]
	v_pk_mul_f32 v[58:59], v[58:59], v[70:71] op_sel_hi:[1,0]
	v_pk_mul_f32 v[56:57], v[56:57], v[70:71] op_sel_hi:[1,0]
	v_pk_mul_f32 v[54:55], v[54:55], v[70:71] op_sel_hi:[1,0]
	v_pk_mul_f32 v[52:53], v[52:53], v[70:71] op_sel_hi:[1,0]
	v_pk_mul_f32 v[50:51], v[50:51], v[70:71] op_sel_hi:[1,0]
	v_pk_mul_f32 v[48:49], v[48:49], v[70:71] op_sel_hi:[1,0]
	v_pk_mul_f32 v[46:47], v[46:47], v[70:71] op_sel_hi:[1,0]
	v_pk_mul_f32 v[44:45], v[44:45], v[70:71] op_sel_hi:[1,0]
	v_pk_mul_f32 v[42:43], v[42:43], v[70:71] op_sel_hi:[1,0]
	v_pk_mul_f32 v[40:41], v[40:41], v[70:71] op_sel_hi:[1,0]
	v_pk_mul_f32 v[38:39], v[38:39], v[70:71] op_sel_hi:[1,0]
	v_pk_mul_f32 v[36:37], v[36:37], v[70:71] op_sel_hi:[1,0]
	v_pk_mul_f32 v[34:35], v[34:35], v[70:71] op_sel_hi:[1,0]
	v_mul_f32_e32 v221, v221, v70

.LBB0_303:
	s_and_b64 vcc, exec, s[4:5]
	s_cbranch_vccz .LBB0_307
	ds_read_b128 v[66:69], v238
	ds_read_b128 v[98:101], v238 offset:32
	ds_read_b128 v[102:105], v238 offset:64
	ds_read_b128 v[106:109], v238 offset:96
	s_nop 3
	ds_read_b64_tr_b16 v[94:95], v237
	ds_read_b64_tr_b16 v[96:97], v237 offset:1024
	ds_read_b64_tr_b16 v[92:93], v237 offset:1536
	ds_read_b64_tr_b16 v[90:91], v237 offset:512
	ds_read_b64_tr_b16 v[86:87], v237 offset:2048
	ds_read_b64_tr_b16 v[88:89], v237 offset:3072
	ds_read_b64_tr_b16 v[84:85], v237 offset:3584
	ds_read_b64_tr_b16 v[82:83], v237 offset:2560
	s_cmp_eq_u32 s12, s63
	s_cselect_b64 s[4:5], -1, 0
	s_waitcnt lgkmcnt(0)
	v_mfma_f32_32x32x16_bf16 v[66:81], v[66:69], v[142:145], 0
	s_and_b64 vcc, s[4:5], s[38:39]
	v_mfma_f32_32x32x16_bf16 v[66:81], v[98:101], v[138:141], v[66:81]
	v_mfma_f32_32x32x16_bf16 v[66:81], v[102:105], v[134:137], v[66:81]
	v_mfma_f32_32x32x16_bf16 v[66:81], v[106:109], v[130:133], v[66:81]
	s_nop 11
	v_cndmask_b32_e64 v98, v69, v68, s[92:93]
	v_cndmask_b32_e64 v99, v73, v72, s[92:93]
	v_cndmask_b32_e64 v100, v77, v76, s[92:93]
	v_cndmask_b32_e64 v101, v81, v80, s[92:93]
	v_cndmask_b32_e64 v98, v98, v67, s[90:91]
	v_cndmask_b32_e64 v99, v99, v71, s[90:91]
	v_cndmask_b32_e64 v100, v100, v75, s[90:91]
	v_cndmask_b32_e64 v101, v101, v79, s[90:91]
	v_cndmask_b32_e64 v66, v98, v66, s[88:89]
	v_cndmask_b32_e64 v67, v99, v70, s[88:89]
	v_cndmask_b32_e64 v68, v100, v74, s[88:89]
	v_cndmask_b32_e64 v69, v101, v78, s[88:89]
	v_fmamk_f32 v66, v66, 0x3e38aa3b, v214
	v_fmamk_f32 v67, v67, 0x3e38aa3b, v214
	v_fmamk_f32 v68, v68, 0x3e38aa3b, v214
	v_fmamk_f32 v69, v69, 0x3e38aa3b, v214
	v_cndmask_b32_e32 v66, v66, v229, vcc
	s_and_b64 vcc, s[4:5], s[40:41]
	v_cndmask_b32_e32 v67, v67, v229, vcc
	s_and_b64 vcc, s[4:5], s[42:43]
	v_cndmask_b32_e32 v68, v68, v229, vcc
	s_and_b64 vcc, s[4:5], s[44:45]
	v_cndmask_b32_e32 v69, v69, v229, vcc
	v_max_f32_e32 v70, v69, v69
	v_max_f32_e32 v71, v68, v68
	v_max_f32_e32 v70, v71, v70
	v_max3_f32 v70, v66, v67, v70
	v_cmp_gt_f32_e32 vcc, v70, v236
	s_cbranch_vccz .LBB0_306
	v_and_b32_e32 v72, 64, v228
	v_xor_b32_e32 v71, 32, v228
	v_add_u32_e32 v72, 64, v72
	v_cmp_lt_i32_e32 vcc, v71, v72
	s_nop 1
	v_cndmask_b32_e32 v71, v228, v71, vcc
	v_lshlrev_b32_e32 v71, 2, v71
	ds_bpermute_b32 v71, v71, v70
	v_max_f32_e32 v70, v70, v70
	s_waitcnt lgkmcnt(0)
	v_max_f32_e32 v71, v71, v71
	v_max_f32_e32 v70, v70, v71
	v_cmp_gt_f32_e32 vcc, v70, v236
	s_nop 1
	v_cndmask_b32_e32 v71, v222, v70, vcc
	v_sub_f32_e32 v70, v222, v71
	v_exp_f32_e32 v70, v70
	v_mov_b32_e32 v222, v71
	v_pk_mul_f32 v[32:33], v[32:33], v[70:71] op_sel_hi:[1,0]
	v_pk_mul_f32 v[30:31], v[30:31], v[70:71] op_sel_hi:[1,0]
	v_pk_mul_f32 v[28:29], v[28:29], v[70:71] op_sel_hi:[1,0]
	v_pk_mul_f32 v[26:27], v[26:27], v[70:71] op_sel_hi:[1,0]
	v_pk_mul_f32 v[24:25], v[24:25], v[70:71] op_sel_hi:[1,0]
	v_pk_mul_f32 v[22:23], v[22:23], v[70:71] op_sel_hi:[1,0]
	v_pk_mul_f32 v[20:21], v[20:21], v[70:71] op_sel_hi:[1,0]
	v_pk_mul_f32 v[18:19], v[18:19], v[70:71] op_sel_hi:[1,0]
	v_pk_mul_f32 v[16:17], v[16:17], v[70:71] op_sel_hi:[1,0]
	v_pk_mul_f32 v[14:15], v[14:15], v[70:71] op_sel_hi:[1,0]
	v_pk_mul_f32 v[12:13], v[12:13], v[70:71] op_sel_hi:[1,0]
	v_pk_mul_f32 v[10:11], v[10:11], v[70:71] op_sel_hi:[1,0]
	v_pk_mul_f32 v[8:9], v[8:9], v[70:71] op_sel_hi:[1,0]
	v_pk_mul_f32 v[6:7], v[6:7], v[70:71] op_sel_hi:[1,0]
	v_pk_mul_f32 v[4:5], v[4:5], v[70:71] op_sel_hi:[1,0]
	v_pk_mul_f32 v[2:3], v[2:3], v[70:71] op_sel_hi:[1,0]
	v_mul_f32_e32 v220, v220, v70
